# prep: x->bf16+sumsq row pass software-pipelined by hand (3 rows of loads in flight per wave)
# baseline (speedup 1.0000x reference)
; __device__ __forceinline__ unsigned cvt_pk_bf16(float lo, float hi) { unsigned r; asm("v_cvt_pk_bf16_f32 %0, %1, %2" : "=v"(r) : "v"(lo), "v"(hi)); return r; }
; __device__ __forceinline__ void phase_prep(const Params& p, LAS unsigned char* lds) {
;     ...
;     for (int row = blockIdx.x * 8 + wid; row < T; row += gridDim.x * 16) {
;         const int row2 = row + gridDim.x * 8; const bool has2 = row2 < T;
;         const float* xr = row < TP ? p.x_prompt + (size_t)row * 2048 : p.x_sample + (size_t)(row - TP) * 2048;
;         const float* xr2 = has2 ? (row2 < TP ? p.x_prompt + (size_t)row2 * 2048 : p.x_sample + (size_t)(row2 - TP) * 2048) : xr;
;         f32x4 va[8], vb[8];
; #pragma unroll
;         for (int j = 0; j < 8; ++j) { va[j] = *(const f32x4*)(xr + j * 256 + lane * 4); vb[j] = *(const f32x4*)(xr2 + j * 256 + lane * 4); }
;         float ss = 0.f, ss2 = 0.f;
; #pragma unroll
;         for (int j = 0; j < 8; ++j) {
;             ss += va[j][0] * va[j][0] + va[j][1] * va[j][1] + va[j][2] * va[j][2] + va[j][3] * va[j][3];
;             ss2 += vb[j][0] * vb[j][0] + vb[j][1] * vb[j][1] + vb[j][2] * vb[j][2] + vb[j][3] * vb[j][3];
;             u32x2 w; w.x = cvt_pk_bf16(va[j][0], va[j][1]); w.y = cvt_pk_bf16(va[j][2], va[j][3]);
;             *(u32x2*)(xb + (size_t)row * 2048 + j * 256 + lane * 4) = w;
;             if (has2) { u32x2 w2; w2.x = cvt_pk_bf16(vb[j][0], vb[j][1]); w2.y = cvt_pk_bf16(vb[j][2], vb[j][3]);
;                 *(u32x2*)(xb + (size_t)row2 * 2048 + j * 256 + lane * 4) = w2; }
;         }
; #pragma unroll
;         for (int o = 32; o >= 1; o >>= 1) { ss += __shfl_xor(ss, o); ss2 += __shfl_xor(ss2, o); }
;         if (lane == 0) { sumsq[row] = (u64)(ss * SS_SCALE); if (has2) sumsq[row2] = (u64)(ss2 * SS_SCALE); }
.LBB0_19:
	v_readfirstlane_b32 s18, v66
	v_lshlrev_b32_e32 v150, 4, v86
	v_add_u32_e32 v151, 0x1000, v150
	v_lshlrev_b32_e32 v152, 3, v86
	v_mov_b32_e32 v153, 0
	v_xor_b32_e32 v154, 32, v86
	v_lshlrev_b32_e32 v154, 2, v154
	v_xor_b32_e32 v155, 16, v86
	v_lshlrev_b32_e32 v155, 2, v155
	v_xor_b32_e32 v156, 8, v86
	v_lshlrev_b32_e32 v156, 2, v156
	v_xor_b32_e32 v157, 4, v86
	v_lshlrev_b32_e32 v157, 2, v157
	v_xor_b32_e32 v158, 2, v86
	v_lshlrev_b32_e32 v158, 2, v158
	v_xor_b32_e32 v159, 1, v86
	v_lshlrev_b32_e32 v159, 2, v159
	s_lshl_b32 s19, s18, 13
	s_add_u32 s12, s60, s19
	s_addc_u32 s13, s61, 0
	s_lshl_b32 s19, s18, 12
	s_add_u32 s14, s58, s19
	s_addc_u32 s15, s59, 0
	s_add_u32 s14, s14, 0x10800000
	s_addc_u32 s15, s15, 0
	s_lshl_b32 s19, s18, 3
	s_add_u32 s16, s80, s19
	s_addc_u32 s17, s81, 0
	global_load_dwordx4 v[2:5], v150, s[12:13]
	global_load_dwordx4 v[6:9], v150, s[12:13] offset:1024
	global_load_dwordx4 v[10:13], v150, s[12:13] offset:2048
	global_load_dwordx4 v[14:17], v150, s[12:13] offset:3072
	global_load_dwordx4 v[18:21], v151, s[12:13]
	global_load_dwordx4 v[22:25], v151, s[12:13] offset:1024
	global_load_dwordx4 v[26:29], v151, s[12:13] offset:2048
	global_load_dwordx4 v[30:33], v151, s[12:13] offset:3072
	s_add_u32 s12, s12, 0x1000000
	s_addc_u32 s13, s13, 0
	global_load_dwordx4 v[100:103], v150, s[12:13]
	global_load_dwordx4 v[104:107], v150, s[12:13] offset:1024
	global_load_dwordx4 v[108:111], v150, s[12:13] offset:2048
	global_load_dwordx4 v[112:115], v150, s[12:13] offset:3072
	global_load_dwordx4 v[116:119], v151, s[12:13]
	global_load_dwordx4 v[120:123], v151, s[12:13] offset:1024
	global_load_dwordx4 v[124:127], v151, s[12:13] offset:2048
	global_load_dwordx4 v[128:131], v151, s[12:13] offset:3072
	s_add_u32 s12, s12, 0x1000000
	s_addc_u32 s13, s13, 0
	global_load_dwordx4 v[164:167], v150, s[12:13]
	global_load_dwordx4 v[168:171], v150, s[12:13] offset:1024
	global_load_dwordx4 v[172:175], v150, s[12:13] offset:2048
	global_load_dwordx4 v[176:179], v150, s[12:13] offset:3072
	global_load_dwordx4 v[180:183], v151, s[12:13]
	global_load_dwordx4 v[184:187], v151, s[12:13] offset:1024
	global_load_dwordx4 v[188:191], v151, s[12:13] offset:2048
	global_load_dwordx4 v[192:195], v151, s[12:13] offset:3072
	s_add_u32 s12, s12, 0x1000000
	s_addc_u32 s13, s13, 0
	s_waitcnt vmcnt(16)
	v_cvt_pk_bf16_f32 v132, v2, v3
	v_cvt_pk_bf16_f32 v133, v4, v5
	global_store_dwordx2 v152, v[132:133], s[14:15]
	v_cvt_pk_bf16_f32 v134, v6, v7
	v_cvt_pk_bf16_f32 v135, v8, v9
	global_store_dwordx2 v152, v[134:135], s[14:15] offset:512
	v_cvt_pk_bf16_f32 v136, v10, v11
	v_cvt_pk_bf16_f32 v137, v12, v13
	global_store_dwordx2 v152, v[136:137], s[14:15] offset:1024
	v_cvt_pk_bf16_f32 v138, v14, v15
	v_cvt_pk_bf16_f32 v139, v16, v17
	global_store_dwordx2 v152, v[138:139], s[14:15] offset:1536
	v_cvt_pk_bf16_f32 v140, v18, v19
	v_cvt_pk_bf16_f32 v141, v20, v21
	global_store_dwordx2 v152, v[140:141], s[14:15] offset:2048
	v_cvt_pk_bf16_f32 v142, v22, v23
	v_cvt_pk_bf16_f32 v143, v24, v25
	global_store_dwordx2 v152, v[142:143], s[14:15] offset:2560
	v_cvt_pk_bf16_f32 v144, v26, v27
	v_cvt_pk_bf16_f32 v145, v28, v29
	global_store_dwordx2 v152, v[144:145], s[14:15] offset:3072
	v_cvt_pk_bf16_f32 v146, v30, v31
	v_cvt_pk_bf16_f32 v147, v32, v33
	global_store_dwordx2 v152, v[146:147], s[14:15] offset:3584
	v_mul_f32_e32 v3, v3, v3
	v_fmac_f32_e32 v3, v2, v2
	v_fmac_f32_e32 v3, v4, v4
	v_fmac_f32_e32 v3, v5, v5
	v_mul_f32_e32 v7, v7, v7
	v_fmac_f32_e32 v7, v6, v6
	v_fmac_f32_e32 v7, v8, v8
	v_fmac_f32_e32 v7, v9, v9
	v_mul_f32_e32 v11, v11, v11
	v_fmac_f32_e32 v11, v10, v10
	v_fmac_f32_e32 v11, v12, v12
	v_fmac_f32_e32 v11, v13, v13
	v_mul_f32_e32 v15, v15, v15
	v_fmac_f32_e32 v15, v14, v14
	v_fmac_f32_e32 v15, v16, v16
	v_fmac_f32_e32 v15, v17, v17
	v_mul_f32_e32 v19, v19, v19
	v_fmac_f32_e32 v19, v18, v18
	v_fmac_f32_e32 v19, v20, v20
	v_fmac_f32_e32 v19, v21, v21
	v_mul_f32_e32 v23, v23, v23
	v_fmac_f32_e32 v23, v22, v22
	v_fmac_f32_e32 v23, v24, v24
	v_fmac_f32_e32 v23, v25, v25
	v_mul_f32_e32 v27, v27, v27
	v_fmac_f32_e32 v27, v26, v26
	v_fmac_f32_e32 v27, v28, v28
	v_fmac_f32_e32 v27, v29, v29
	v_mul_f32_e32 v31, v31, v31
	v_fmac_f32_e32 v31, v30, v30
	v_fmac_f32_e32 v31, v32, v32
	v_fmac_f32_e32 v31, v33, v33
	v_add_f32_e32 v160, v3, v7
	v_add_f32_e32 v160, v160, v11
	v_add_f32_e32 v160, v160, v15
	v_add_f32_e32 v160, v160, v19
	v_add_f32_e32 v160, v160, v23
	v_add_f32_e32 v160, v160, v27
	v_add_f32_e32 v160, v160, v31
	ds_bpermute_b32 v161, v154, v160
	s_waitcnt lgkmcnt(0)
	v_add_f32_e32 v160, v160, v161
	ds_bpermute_b32 v161, v155, v160
	s_waitcnt lgkmcnt(0)
	v_add_f32_e32 v160, v160, v161
	ds_bpermute_b32 v161, v156, v160
	s_waitcnt lgkmcnt(0)
	v_add_f32_e32 v160, v160, v161
	ds_bpermute_b32 v161, v157, v160
	s_waitcnt lgkmcnt(0)
	v_add_f32_e32 v160, v160, v161
	ds_bpermute_b32 v161, v158, v160
	s_waitcnt lgkmcnt(0)
	v_add_f32_e32 v160, v160, v161
	ds_bpermute_b32 v161, v159, v160
	s_waitcnt lgkmcnt(0)
	v_add_f32_e32 v160, v160, v161
	s_and_saveexec_b64 s[20:21], s[4:5]
	v_mul_f32_e32 v162, 0x49800000, v160
	v_trunc_f32_e32 v162, v162
	v_mul_f32_e32 v163, 0x2f800000, v162
	v_floor_f32_e32 v163, v163
	v_fmac_f32_e32 v162, 0xcf800000, v163
	v_cvt_u32_f32_e32 v162, v162
	v_cvt_u32_f32_e32 v163, v163
	global_store_dwordx2 v153, v[162:163], s[16:17]
	s_or_b64 exec, exec, s[20:21]
	s_add_u32 s14, s14, 0x800000
	s_addc_u32 s15, s15, 0
	s_add_u32 s16, s16, 0x4000
	s_addc_u32 s17, s17, 0
	global_load_dwordx4 v[2:5], v150, s[12:13]
	global_load_dwordx4 v[6:9], v150, s[12:13] offset:1024
	global_load_dwordx4 v[10:13], v150, s[12:13] offset:2048
	global_load_dwordx4 v[14:17], v150, s[12:13] offset:3072
	global_load_dwordx4 v[18:21], v151, s[12:13]
	global_load_dwordx4 v[22:25], v151, s[12:13] offset:1024
	global_load_dwordx4 v[26:29], v151, s[12:13] offset:2048
	global_load_dwordx4 v[30:33], v151, s[12:13] offset:3072
	s_add_u32 s12, s12, 0x1000000
	s_addc_u32 s13, s13, 0
	s_waitcnt vmcnt(25)
; __device__ __forceinline__ unsigned cvt_pk_bf16(float lo, float hi) { unsigned r; asm("v_cvt_pk_bf16_f32 %0, %1, %2" : "=v"(r) : "v"(lo), "v"(hi)); return r; }
; __device__ __forceinline__ void phase_prep(const Params& p, LAS unsigned char* lds) {
;     ...
;         for (int j = 0; j < 8; ++j) { va[j] = *(const f32x4*)(xr + j * 256 + lane * 4); vb[j] = *(const f32x4*)(xr2 + j * 256 + lane * 4); }
;         float ss = 0.f, ss2 = 0.f;
; #pragma unroll
;         for (int j = 0; j < 8; ++j) {
;             ss += va[j][0] * va[j][0] + va[j][1] * va[j][1] + va[j][2] * va[j][2] + va[j][3] * va[j][3];
;             ss2 += vb[j][0] * vb[j][0] + vb[j][1] * vb[j][1] + vb[j][2] * vb[j][2] + vb[j][3] * vb[j][3];
;             u32x2 w; w.x = cvt_pk_bf16(va[j][0], va[j][1]); w.y = cvt_pk_bf16(va[j][2], va[j][3]);
;             *(u32x2*)(xb + (size_t)row * 2048 + j * 256 + lane * 4) = w;
;             if (has2) { u32x2 w2; w2.x = cvt_pk_bf16(vb[j][0], vb[j][1]); w2.y = cvt_pk_bf16(vb[j][2], vb[j][3]);
;                 *(u32x2*)(xb + (size_t)row2 * 2048 + j * 256 + lane * 4) = w2; }
;         }
; #pragma unroll
;         for (int o = 32; o >= 1; o >>= 1) { ss += __shfl_xor(ss, o); ss2 += __shfl_xor(ss2, o); }
;         if (lane == 0) { sumsq[row] = (u64)(ss * SS_SCALE); if (has2) sumsq[row2] = (u64)(ss2 * SS_SCALE); }
	v_cvt_pk_bf16_f32 v132, v100, v101
	v_cvt_pk_bf16_f32 v133, v102, v103
	global_store_dwordx2 v152, v[132:133], s[14:15]
	v_cvt_pk_bf16_f32 v134, v104, v105
	v_cvt_pk_bf16_f32 v135, v106, v107
	global_store_dwordx2 v152, v[134:135], s[14:15] offset:512
	v_cvt_pk_bf16_f32 v136, v108, v109
	v_cvt_pk_bf16_f32 v137, v110, v111
	global_store_dwordx2 v152, v[136:137], s[14:15] offset:1024
	v_cvt_pk_bf16_f32 v138, v112, v113
	v_cvt_pk_bf16_f32 v139, v114, v115
	global_store_dwordx2 v152, v[138:139], s[14:15] offset:1536
	v_cvt_pk_bf16_f32 v140, v116, v117
	v_cvt_pk_bf16_f32 v141, v118, v119
	global_store_dwordx2 v152, v[140:141], s[14:15] offset:2048
	v_cvt_pk_bf16_f32 v142, v120, v121
	v_cvt_pk_bf16_f32 v143, v122, v123
	global_store_dwordx2 v152, v[142:143], s[14:15] offset:2560
	v_cvt_pk_bf16_f32 v144, v124, v125
	v_cvt_pk_bf16_f32 v145, v126, v127
	global_store_dwordx2 v152, v[144:145], s[14:15] offset:3072
	v_cvt_pk_bf16_f32 v146, v128, v129
	v_cvt_pk_bf16_f32 v147, v130, v131
	global_store_dwordx2 v152, v[146:147], s[14:15] offset:3584
	v_mul_f32_e32 v101, v101, v101
	v_fmac_f32_e32 v101, v100, v100
	v_fmac_f32_e32 v101, v102, v102
	v_fmac_f32_e32 v101, v103, v103
	v_mul_f32_e32 v105, v105, v105
	v_fmac_f32_e32 v105, v104, v104
	v_fmac_f32_e32 v105, v106, v106
	v_fmac_f32_e32 v105, v107, v107
	v_mul_f32_e32 v109, v109, v109
	v_fmac_f32_e32 v109, v108, v108
	v_fmac_f32_e32 v109, v110, v110
	v_fmac_f32_e32 v109, v111, v111
	v_mul_f32_e32 v113, v113, v113
	v_fmac_f32_e32 v113, v112, v112
	v_fmac_f32_e32 v113, v114, v114
	v_fmac_f32_e32 v113, v115, v115
	v_mul_f32_e32 v117, v117, v117
	v_fmac_f32_e32 v117, v116, v116
	v_fmac_f32_e32 v117, v118, v118
	v_fmac_f32_e32 v117, v119, v119
	v_mul_f32_e32 v121, v121, v121
	v_fmac_f32_e32 v121, v120, v120
	v_fmac_f32_e32 v121, v122, v122
	v_fmac_f32_e32 v121, v123, v123
	v_mul_f32_e32 v125, v125, v125
	v_fmac_f32_e32 v125, v124, v124
	v_fmac_f32_e32 v125, v126, v126
	v_fmac_f32_e32 v125, v127, v127
	v_mul_f32_e32 v129, v129, v129
	v_fmac_f32_e32 v129, v128, v128
	v_fmac_f32_e32 v129, v130, v130
	v_fmac_f32_e32 v129, v131, v131
	v_add_f32_e32 v160, v101, v105
	v_add_f32_e32 v160, v160, v109
	v_add_f32_e32 v160, v160, v113
	v_add_f32_e32 v160, v160, v117
	v_add_f32_e32 v160, v160, v121
	v_add_f32_e32 v160, v160, v125
	v_add_f32_e32 v160, v160, v129
	ds_bpermute_b32 v161, v154, v160
	s_waitcnt lgkmcnt(0)
	v_add_f32_e32 v160, v160, v161
	ds_bpermute_b32 v161, v155, v160
	s_waitcnt lgkmcnt(0)
	v_add_f32_e32 v160, v160, v161
	ds_bpermute_b32 v161, v156, v160
	s_waitcnt lgkmcnt(0)
	v_add_f32_e32 v160, v160, v161
	ds_bpermute_b32 v161, v157, v160
	s_waitcnt lgkmcnt(0)
	v_add_f32_e32 v160, v160, v161
	ds_bpermute_b32 v161, v158, v160
	s_waitcnt lgkmcnt(0)
	v_add_f32_e32 v160, v160, v161
	ds_bpermute_b32 v161, v159, v160
	s_waitcnt lgkmcnt(0)
	v_add_f32_e32 v160, v160, v161
	s_and_saveexec_b64 s[20:21], s[4:5]
	v_mul_f32_e32 v162, 0x49800000, v160
	v_trunc_f32_e32 v162, v162
	v_mul_f32_e32 v163, 0x2f800000, v162
	v_floor_f32_e32 v163, v163
	v_fmac_f32_e32 v162, 0xcf800000, v163
	v_cvt_u32_f32_e32 v162, v162
	v_cvt_u32_f32_e32 v163, v163
	global_store_dwordx2 v153, v[162:163], s[16:17]
	s_or_b64 exec, exec, s[20:21]
	s_add_u32 s14, s14, 0x800000
	s_addc_u32 s15, s15, 0
	s_add_u32 s16, s16, 0x4000
	s_addc_u32 s17, s17, 0
	global_load_dwordx4 v[100:103], v150, s[12:13]
	global_load_dwordx4 v[104:107], v150, s[12:13] offset:1024
	global_load_dwordx4 v[108:111], v150, s[12:13] offset:2048
	global_load_dwordx4 v[112:115], v150, s[12:13] offset:3072
	global_load_dwordx4 v[116:119], v151, s[12:13]
	global_load_dwordx4 v[120:123], v151, s[12:13] offset:1024
	global_load_dwordx4 v[124:127], v151, s[12:13] offset:2048
	global_load_dwordx4 v[128:131], v151, s[12:13] offset:3072
	s_add_u32 s12, s12, 0x1000000
	s_addc_u32 s13, s13, 0
	s_waitcnt vmcnt(34)
	v_cvt_pk_bf16_f32 v132, v164, v165
	v_cvt_pk_bf16_f32 v133, v166, v167
	global_store_dwordx2 v152, v[132:133], s[14:15]
	v_cvt_pk_bf16_f32 v134, v168, v169
	v_cvt_pk_bf16_f32 v135, v170, v171
	global_store_dwordx2 v152, v[134:135], s[14:15] offset:512
	v_cvt_pk_bf16_f32 v136, v172, v173
	v_cvt_pk_bf16_f32 v137, v174, v175
	global_store_dwordx2 v152, v[136:137], s[14:15] offset:1024
	v_cvt_pk_bf16_f32 v138, v176, v177
	v_cvt_pk_bf16_f32 v139, v178, v179
	global_store_dwordx2 v152, v[138:139], s[14:15] offset:1536
	v_cvt_pk_bf16_f32 v140, v180, v181
	v_cvt_pk_bf16_f32 v141, v182, v183
	global_store_dwordx2 v152, v[140:141], s[14:15] offset:2048
	v_cvt_pk_bf16_f32 v142, v184, v185
	v_cvt_pk_bf16_f32 v143, v186, v187
	global_store_dwordx2 v152, v[142:143], s[14:15] offset:2560
	v_cvt_pk_bf16_f32 v144, v188, v189
	v_cvt_pk_bf16_f32 v145, v190, v191
	global_store_dwordx2 v152, v[144:145], s[14:15] offset:3072
	v_cvt_pk_bf16_f32 v146, v192, v193
	v_cvt_pk_bf16_f32 v147, v194, v195
	global_store_dwordx2 v152, v[146:147], s[14:15] offset:3584
	v_mul_f32_e32 v165, v165, v165
	v_fmac_f32_e32 v165, v164, v164
	v_fmac_f32_e32 v165, v166, v166
	v_fmac_f32_e32 v165, v167, v167
	v_mul_f32_e32 v169, v169, v169
	v_fmac_f32_e32 v169, v168, v168
	v_fmac_f32_e32 v169, v170, v170
	v_fmac_f32_e32 v169, v171, v171
	v_mul_f32_e32 v173, v173, v173
	v_fmac_f32_e32 v173, v172, v172
	v_fmac_f32_e32 v173, v174, v174
	v_fmac_f32_e32 v173, v175, v175
	v_mul_f32_e32 v177, v177, v177
	v_fmac_f32_e32 v177, v176, v176
	v_fmac_f32_e32 v177, v178, v178
	v_fmac_f32_e32 v177, v179, v179
	v_mul_f32_e32 v181, v181, v181
	v_fmac_f32_e32 v181, v180, v180
	v_fmac_f32_e32 v181, v182, v182
	v_fmac_f32_e32 v181, v183, v183
	v_mul_f32_e32 v185, v185, v185
	v_fmac_f32_e32 v185, v184, v184
	v_fmac_f32_e32 v185, v186, v186
	v_fmac_f32_e32 v185, v187, v187
	v_mul_f32_e32 v189, v189, v189
	v_fmac_f32_e32 v189, v188, v188
	v_fmac_f32_e32 v189, v190, v190
	v_fmac_f32_e32 v189, v191, v191
	v_mul_f32_e32 v193, v193, v193
	v_fmac_f32_e32 v193, v192, v192
	v_fmac_f32_e32 v193, v194, v194
	v_fmac_f32_e32 v193, v195, v195
	v_add_f32_e32 v160, v165, v169
	v_add_f32_e32 v160, v160, v173
	v_add_f32_e32 v160, v160, v177
	v_add_f32_e32 v160, v160, v181
	v_add_f32_e32 v160, v160, v185
	v_add_f32_e32 v160, v160, v189
	v_add_f32_e32 v160, v160, v193
	ds_bpermute_b32 v161, v154, v160
	s_waitcnt lgkmcnt(0)
; __device__ __forceinline__ unsigned cvt_pk_bf16(float lo, float hi) { unsigned r; asm("v_cvt_pk_bf16_f32 %0, %1, %2" : "=v"(r) : "v"(lo), "v"(hi)); return r; }
; __device__ __forceinline__ void phase_prep(const Params& p, LAS unsigned char* lds) {
;     ...
;         for (int j = 0; j < 8; ++j) { va[j] = *(const f32x4*)(xr + j * 256 + lane * 4); vb[j] = *(const f32x4*)(xr2 + j * 256 + lane * 4); }
;         float ss = 0.f, ss2 = 0.f;
; #pragma unroll
;         for (int j = 0; j < 8; ++j) {
;             ss += va[j][0] * va[j][0] + va[j][1] * va[j][1] + va[j][2] * va[j][2] + va[j][3] * va[j][3];
;             ss2 += vb[j][0] * vb[j][0] + vb[j][1] * vb[j][1] + vb[j][2] * vb[j][2] + vb[j][3] * vb[j][3];
;             u32x2 w; w.x = cvt_pk_bf16(va[j][0], va[j][1]); w.y = cvt_pk_bf16(va[j][2], va[j][3]);
;             *(u32x2*)(xb + (size_t)row * 2048 + j * 256 + lane * 4) = w;
;             if (has2) { u32x2 w2; w2.x = cvt_pk_bf16(vb[j][0], vb[j][1]); w2.y = cvt_pk_bf16(vb[j][2], vb[j][3]);
;                 *(u32x2*)(xb + (size_t)row2 * 2048 + j * 256 + lane * 4) = w2; }
;         }
; #pragma unroll
;         for (int o = 32; o >= 1; o >>= 1) { ss += __shfl_xor(ss, o); ss2 += __shfl_xor(ss2, o); }
;         if (lane == 0) { sumsq[row] = (u64)(ss * SS_SCALE); if (has2) sumsq[row2] = (u64)(ss2 * SS_SCALE); }
	v_add_f32_e32 v160, v160, v161
	ds_bpermute_b32 v161, v155, v160
	s_waitcnt lgkmcnt(0)
	v_add_f32_e32 v160, v160, v161
	ds_bpermute_b32 v161, v156, v160
	s_waitcnt lgkmcnt(0)
	v_add_f32_e32 v160, v160, v161
	ds_bpermute_b32 v161, v157, v160
	s_waitcnt lgkmcnt(0)
	v_add_f32_e32 v160, v160, v161
	ds_bpermute_b32 v161, v158, v160
	s_waitcnt lgkmcnt(0)
	v_add_f32_e32 v160, v160, v161
	ds_bpermute_b32 v161, v159, v160
	s_waitcnt lgkmcnt(0)
	v_add_f32_e32 v160, v160, v161
	s_and_saveexec_b64 s[20:21], s[4:5]
	v_mul_f32_e32 v162, 0x49800000, v160
	v_trunc_f32_e32 v162, v162
	v_mul_f32_e32 v163, 0x2f800000, v162
	v_floor_f32_e32 v163, v163
	v_fmac_f32_e32 v162, 0xcf800000, v163
	v_cvt_u32_f32_e32 v162, v162
	v_cvt_u32_f32_e32 v163, v163
	global_store_dwordx2 v153, v[162:163], s[16:17]
	s_or_b64 exec, exec, s[20:21]
	s_add_u32 s14, s14, 0x800000
	s_addc_u32 s15, s15, 0
	s_add_u32 s16, s16, 0x4000
	s_addc_u32 s17, s17, 0
	global_load_dwordx4 v[164:167], v150, s[12:13]
	global_load_dwordx4 v[168:171], v150, s[12:13] offset:1024
	global_load_dwordx4 v[172:175], v150, s[12:13] offset:2048
	global_load_dwordx4 v[176:179], v150, s[12:13] offset:3072
	global_load_dwordx4 v[180:183], v151, s[12:13]
	global_load_dwordx4 v[184:187], v151, s[12:13] offset:1024
	global_load_dwordx4 v[188:191], v151, s[12:13] offset:2048
	global_load_dwordx4 v[192:195], v151, s[12:13] offset:3072
	s_add_u32 s12, s12, 0x1000000
	s_addc_u32 s13, s13, 0
	s_waitcnt vmcnt(34)
	v_cvt_pk_bf16_f32 v132, v2, v3
	v_cvt_pk_bf16_f32 v133, v4, v5
	global_store_dwordx2 v152, v[132:133], s[14:15]
	v_cvt_pk_bf16_f32 v134, v6, v7
	v_cvt_pk_bf16_f32 v135, v8, v9
	global_store_dwordx2 v152, v[134:135], s[14:15] offset:512
	v_cvt_pk_bf16_f32 v136, v10, v11
	v_cvt_pk_bf16_f32 v137, v12, v13
	global_store_dwordx2 v152, v[136:137], s[14:15] offset:1024
	v_cvt_pk_bf16_f32 v138, v14, v15
	v_cvt_pk_bf16_f32 v139, v16, v17
	global_store_dwordx2 v152, v[138:139], s[14:15] offset:1536
	v_cvt_pk_bf16_f32 v140, v18, v19
	v_cvt_pk_bf16_f32 v141, v20, v21
	global_store_dwordx2 v152, v[140:141], s[14:15] offset:2048
	v_cvt_pk_bf16_f32 v142, v22, v23
	v_cvt_pk_bf16_f32 v143, v24, v25
	global_store_dwordx2 v152, v[142:143], s[14:15] offset:2560
	v_cvt_pk_bf16_f32 v144, v26, v27
	v_cvt_pk_bf16_f32 v145, v28, v29
	global_store_dwordx2 v152, v[144:145], s[14:15] offset:3072
	v_cvt_pk_bf16_f32 v146, v30, v31
	v_cvt_pk_bf16_f32 v147, v32, v33
	global_store_dwordx2 v152, v[146:147], s[14:15] offset:3584
	v_mul_f32_e32 v3, v3, v3
	v_fmac_f32_e32 v3, v2, v2
	v_fmac_f32_e32 v3, v4, v4
	v_fmac_f32_e32 v3, v5, v5
	v_mul_f32_e32 v7, v7, v7
	v_fmac_f32_e32 v7, v6, v6
	v_fmac_f32_e32 v7, v8, v8
	v_fmac_f32_e32 v7, v9, v9
	v_mul_f32_e32 v11, v11, v11
	v_fmac_f32_e32 v11, v10, v10
	v_fmac_f32_e32 v11, v12, v12
	v_fmac_f32_e32 v11, v13, v13
	v_mul_f32_e32 v15, v15, v15
	v_fmac_f32_e32 v15, v14, v14
	v_fmac_f32_e32 v15, v16, v16
	v_fmac_f32_e32 v15, v17, v17
	v_mul_f32_e32 v19, v19, v19
	v_fmac_f32_e32 v19, v18, v18
	v_fmac_f32_e32 v19, v20, v20
	v_fmac_f32_e32 v19, v21, v21
	v_mul_f32_e32 v23, v23, v23
	v_fmac_f32_e32 v23, v22, v22
	v_fmac_f32_e32 v23, v24, v24
	v_fmac_f32_e32 v23, v25, v25
	v_mul_f32_e32 v27, v27, v27
	v_fmac_f32_e32 v27, v26, v26
	v_fmac_f32_e32 v27, v28, v28
	v_fmac_f32_e32 v27, v29, v29
	v_mul_f32_e32 v31, v31, v31
	v_fmac_f32_e32 v31, v30, v30
	v_fmac_f32_e32 v31, v32, v32
	v_fmac_f32_e32 v31, v33, v33
	v_add_f32_e32 v160, v3, v7
	v_add_f32_e32 v160, v160, v11
	v_add_f32_e32 v160, v160, v15
	v_add_f32_e32 v160, v160, v19
	v_add_f32_e32 v160, v160, v23
	v_add_f32_e32 v160, v160, v27
	v_add_f32_e32 v160, v160, v31
	ds_bpermute_b32 v161, v154, v160
	s_waitcnt lgkmcnt(0)
	v_add_f32_e32 v160, v160, v161
	ds_bpermute_b32 v161, v155, v160
	s_waitcnt lgkmcnt(0)
	v_add_f32_e32 v160, v160, v161
	ds_bpermute_b32 v161, v156, v160
	s_waitcnt lgkmcnt(0)
	v_add_f32_e32 v160, v160, v161
	ds_bpermute_b32 v161, v157, v160
	s_waitcnt lgkmcnt(0)
	v_add_f32_e32 v160, v160, v161
	ds_bpermute_b32 v161, v158, v160
	s_waitcnt lgkmcnt(0)
	v_add_f32_e32 v160, v160, v161
	ds_bpermute_b32 v161, v159, v160
	s_waitcnt lgkmcnt(0)
	v_add_f32_e32 v160, v160, v161
	s_and_saveexec_b64 s[20:21], s[4:5]
	v_mul_f32_e32 v162, 0x49800000, v160
	v_trunc_f32_e32 v162, v162
	v_mul_f32_e32 v163, 0x2f800000, v162
	v_floor_f32_e32 v163, v163
	v_fmac_f32_e32 v162, 0xcf800000, v163
	v_cvt_u32_f32_e32 v162, v162
	v_cvt_u32_f32_e32 v163, v163
	global_store_dwordx2 v153, v[162:163], s[16:17]
	s_or_b64 exec, exec, s[20:21]
	s_add_u32 s14, s14, 0x800000
	s_addc_u32 s15, s15, 0
	s_add_u32 s16, s16, 0x4000
	s_addc_u32 s17, s17, 0
	global_load_dwordx4 v[2:5], v150, s[12:13]
	global_load_dwordx4 v[6:9], v150, s[12:13] offset:1024
	global_load_dwordx4 v[10:13], v150, s[12:13] offset:2048
	global_load_dwordx4 v[14:17], v150, s[12:13] offset:3072
	global_load_dwordx4 v[18:21], v151, s[12:13]
	global_load_dwordx4 v[22:25], v151, s[12:13] offset:1024
	global_load_dwordx4 v[26:29], v151, s[12:13] offset:2048
	global_load_dwordx4 v[30:33], v151, s[12:13] offset:3072
	s_add_u32 s12, s12, 0x1000000
	s_addc_u32 s13, s13, 0
	s_waitcnt vmcnt(34)
; __device__ __forceinline__ unsigned cvt_pk_bf16(float lo, float hi) { unsigned r; asm("v_cvt_pk_bf16_f32 %0, %1, %2" : "=v"(r) : "v"(lo), "v"(hi)); return r; }
; __device__ __forceinline__ void phase_prep(const Params& p, LAS unsigned char* lds) {
;     ...
;         for (int j = 0; j < 8; ++j) { va[j] = *(const f32x4*)(xr + j * 256 + lane * 4); vb[j] = *(const f32x4*)(xr2 + j * 256 + lane * 4); }
;         float ss = 0.f, ss2 = 0.f;
; #pragma unroll
;         for (int j = 0; j < 8; ++j) {
;             ss += va[j][0] * va[j][0] + va[j][1] * va[j][1] + va[j][2] * va[j][2] + va[j][3] * va[j][3];
;             ss2 += vb[j][0] * vb[j][0] + vb[j][1] * vb[j][1] + vb[j][2] * vb[j][2] + vb[j][3] * vb[j][3];
;             u32x2 w; w.x = cvt_pk_bf16(va[j][0], va[j][1]); w.y = cvt_pk_bf16(va[j][2], va[j][3]);
;             *(u32x2*)(xb + (size_t)row * 2048 + j * 256 + lane * 4) = w;
;             if (has2) { u32x2 w2; w2.x = cvt_pk_bf16(vb[j][0], vb[j][1]); w2.y = cvt_pk_bf16(vb[j][2], vb[j][3]);
;                 *(u32x2*)(xb + (size_t)row2 * 2048 + j * 256 + lane * 4) = w2; }
;         }
; #pragma unroll
;         for (int o = 32; o >= 1; o >>= 1) { ss += __shfl_xor(ss, o); ss2 += __shfl_xor(ss2, o); }
;         if (lane == 0) { sumsq[row] = (u64)(ss * SS_SCALE); if (has2) sumsq[row2] = (u64)(ss2 * SS_SCALE); }
	v_cvt_pk_bf16_f32 v132, v100, v101
	v_cvt_pk_bf16_f32 v133, v102, v103
	global_store_dwordx2 v152, v[132:133], s[14:15]
	v_cvt_pk_bf16_f32 v134, v104, v105
	v_cvt_pk_bf16_f32 v135, v106, v107
	global_store_dwordx2 v152, v[134:135], s[14:15] offset:512
	v_cvt_pk_bf16_f32 v136, v108, v109
	v_cvt_pk_bf16_f32 v137, v110, v111
	global_store_dwordx2 v152, v[136:137], s[14:15] offset:1024
	v_cvt_pk_bf16_f32 v138, v112, v113
	v_cvt_pk_bf16_f32 v139, v114, v115
	global_store_dwordx2 v152, v[138:139], s[14:15] offset:1536
	v_cvt_pk_bf16_f32 v140, v116, v117
	v_cvt_pk_bf16_f32 v141, v118, v119
	global_store_dwordx2 v152, v[140:141], s[14:15] offset:2048
	v_cvt_pk_bf16_f32 v142, v120, v121
	v_cvt_pk_bf16_f32 v143, v122, v123
	global_store_dwordx2 v152, v[142:143], s[14:15] offset:2560
	v_cvt_pk_bf16_f32 v144, v124, v125
	v_cvt_pk_bf16_f32 v145, v126, v127
	global_store_dwordx2 v152, v[144:145], s[14:15] offset:3072
	v_cvt_pk_bf16_f32 v146, v128, v129
	v_cvt_pk_bf16_f32 v147, v130, v131
	global_store_dwordx2 v152, v[146:147], s[14:15] offset:3584
	v_mul_f32_e32 v101, v101, v101
	v_fmac_f32_e32 v101, v100, v100
	v_fmac_f32_e32 v101, v102, v102
	v_fmac_f32_e32 v101, v103, v103
	v_mul_f32_e32 v105, v105, v105
	v_fmac_f32_e32 v105, v104, v104
	v_fmac_f32_e32 v105, v106, v106
	v_fmac_f32_e32 v105, v107, v107
	v_mul_f32_e32 v109, v109, v109
	v_fmac_f32_e32 v109, v108, v108
	v_fmac_f32_e32 v109, v110, v110
	v_fmac_f32_e32 v109, v111, v111
	v_mul_f32_e32 v113, v113, v113
	v_fmac_f32_e32 v113, v112, v112
	v_fmac_f32_e32 v113, v114, v114
	v_fmac_f32_e32 v113, v115, v115
	v_mul_f32_e32 v117, v117, v117
	v_fmac_f32_e32 v117, v116, v116
	v_fmac_f32_e32 v117, v118, v118
	v_fmac_f32_e32 v117, v119, v119
	v_mul_f32_e32 v121, v121, v121
	v_fmac_f32_e32 v121, v120, v120
	v_fmac_f32_e32 v121, v122, v122
	v_fmac_f32_e32 v121, v123, v123
	v_mul_f32_e32 v125, v125, v125
	v_fmac_f32_e32 v125, v124, v124
	v_fmac_f32_e32 v125, v126, v126
	v_fmac_f32_e32 v125, v127, v127
	v_mul_f32_e32 v129, v129, v129
	v_fmac_f32_e32 v129, v128, v128
	v_fmac_f32_e32 v129, v130, v130
	v_fmac_f32_e32 v129, v131, v131
	v_add_f32_e32 v160, v101, v105
	v_add_f32_e32 v160, v160, v109
	v_add_f32_e32 v160, v160, v113
	v_add_f32_e32 v160, v160, v117
	v_add_f32_e32 v160, v160, v121
	v_add_f32_e32 v160, v160, v125
	v_add_f32_e32 v160, v160, v129
	ds_bpermute_b32 v161, v154, v160
	s_waitcnt lgkmcnt(0)
	v_add_f32_e32 v160, v160, v161
	ds_bpermute_b32 v161, v155, v160
	s_waitcnt lgkmcnt(0)
	v_add_f32_e32 v160, v160, v161
	ds_bpermute_b32 v161, v156, v160
	s_waitcnt lgkmcnt(0)
	v_add_f32_e32 v160, v160, v161
	ds_bpermute_b32 v161, v157, v160
	s_waitcnt lgkmcnt(0)
	v_add_f32_e32 v160, v160, v161
	ds_bpermute_b32 v161, v158, v160
	s_waitcnt lgkmcnt(0)
	v_add_f32_e32 v160, v160, v161
	ds_bpermute_b32 v161, v159, v160
	s_waitcnt lgkmcnt(0)
	v_add_f32_e32 v160, v160, v161
	s_and_saveexec_b64 s[20:21], s[4:5]
	v_mul_f32_e32 v162, 0x49800000, v160
	v_trunc_f32_e32 v162, v162
	v_mul_f32_e32 v163, 0x2f800000, v162
	v_floor_f32_e32 v163, v163
	v_fmac_f32_e32 v162, 0xcf800000, v163
	v_cvt_u32_f32_e32 v162, v162
	v_cvt_u32_f32_e32 v163, v163
	global_store_dwordx2 v153, v[162:163], s[16:17]
	s_or_b64 exec, exec, s[20:21]
	s_add_u32 s14, s14, 0x800000
	s_addc_u32 s15, s15, 0
	s_add_u32 s16, s16, 0x4000
	s_addc_u32 s17, s17, 0
	global_load_dwordx4 v[100:103], v150, s[12:13]
	global_load_dwordx4 v[104:107], v150, s[12:13] offset:1024
	global_load_dwordx4 v[108:111], v150, s[12:13] offset:2048
	global_load_dwordx4 v[112:115], v150, s[12:13] offset:3072
	global_load_dwordx4 v[116:119], v151, s[12:13]
	global_load_dwordx4 v[120:123], v151, s[12:13] offset:1024
	global_load_dwordx4 v[124:127], v151, s[12:13] offset:2048
	global_load_dwordx4 v[128:131], v151, s[12:13] offset:3072
	s_add_u32 s12, s12, 0x1000000
	s_addc_u32 s13, s13, 0
	s_waitcnt vmcnt(34)
	v_cvt_pk_bf16_f32 v132, v164, v165
	v_cvt_pk_bf16_f32 v133, v166, v167
	global_store_dwordx2 v152, v[132:133], s[14:15]
	v_cvt_pk_bf16_f32 v134, v168, v169
	v_cvt_pk_bf16_f32 v135, v170, v171
	global_store_dwordx2 v152, v[134:135], s[14:15] offset:512
	v_cvt_pk_bf16_f32 v136, v172, v173
	v_cvt_pk_bf16_f32 v137, v174, v175
	global_store_dwordx2 v152, v[136:137], s[14:15] offset:1024
	v_cvt_pk_bf16_f32 v138, v176, v177
	v_cvt_pk_bf16_f32 v139, v178, v179
	global_store_dwordx2 v152, v[138:139], s[14:15] offset:1536
	v_cvt_pk_bf16_f32 v140, v180, v181
	v_cvt_pk_bf16_f32 v141, v182, v183
	global_store_dwordx2 v152, v[140:141], s[14:15] offset:2048
	v_cvt_pk_bf16_f32 v142, v184, v185
	v_cvt_pk_bf16_f32 v143, v186, v187
	global_store_dwordx2 v152, v[142:143], s[14:15] offset:2560
	v_cvt_pk_bf16_f32 v144, v188, v189
	v_cvt_pk_bf16_f32 v145, v190, v191
	global_store_dwordx2 v152, v[144:145], s[14:15] offset:3072
	v_cvt_pk_bf16_f32 v146, v192, v193
	v_cvt_pk_bf16_f32 v147, v194, v195
	global_store_dwordx2 v152, v[146:147], s[14:15] offset:3584
	v_mul_f32_e32 v165, v165, v165
	v_fmac_f32_e32 v165, v164, v164
	v_fmac_f32_e32 v165, v166, v166
	v_fmac_f32_e32 v165, v167, v167
	v_mul_f32_e32 v169, v169, v169
	v_fmac_f32_e32 v169, v168, v168
	v_fmac_f32_e32 v169, v170, v170
	v_fmac_f32_e32 v169, v171, v171
	v_mul_f32_e32 v173, v173, v173
	v_fmac_f32_e32 v173, v172, v172
	v_fmac_f32_e32 v173, v174, v174
	v_fmac_f32_e32 v173, v175, v175
	v_mul_f32_e32 v177, v177, v177
	v_fmac_f32_e32 v177, v176, v176
	v_fmac_f32_e32 v177, v178, v178
	v_fmac_f32_e32 v177, v179, v179
	v_mul_f32_e32 v181, v181, v181
	v_fmac_f32_e32 v181, v180, v180
	v_fmac_f32_e32 v181, v182, v182
	v_fmac_f32_e32 v181, v183, v183
	v_mul_f32_e32 v185, v185, v185
	v_fmac_f32_e32 v185, v184, v184
	v_fmac_f32_e32 v185, v186, v186
	v_fmac_f32_e32 v185, v187, v187
	v_mul_f32_e32 v189, v189, v189
	v_fmac_f32_e32 v189, v188, v188
	v_fmac_f32_e32 v189, v190, v190
	v_fmac_f32_e32 v189, v191, v191
	v_mul_f32_e32 v193, v193, v193
	v_fmac_f32_e32 v193, v192, v192
	v_fmac_f32_e32 v193, v194, v194
	v_fmac_f32_e32 v193, v195, v195
	v_add_f32_e32 v160, v165, v169
	v_add_f32_e32 v160, v160, v173
	v_add_f32_e32 v160, v160, v177
	v_add_f32_e32 v160, v160, v181
	v_add_f32_e32 v160, v160, v185
	v_add_f32_e32 v160, v160, v189
	v_add_f32_e32 v160, v160, v193
	ds_bpermute_b32 v161, v154, v160
	s_waitcnt lgkmcnt(0)
; __device__ __forceinline__ unsigned cvt_pk_bf16(float lo, float hi) { unsigned r; asm("v_cvt_pk_bf16_f32 %0, %1, %2" : "=v"(r) : "v"(lo), "v"(hi)); return r; }
; __device__ __forceinline__ void phase_prep(const Params& p, LAS unsigned char* lds) {
;     ...
;         for (int j = 0; j < 8; ++j) { va[j] = *(const f32x4*)(xr + j * 256 + lane * 4); vb[j] = *(const f32x4*)(xr2 + j * 256 + lane * 4); }
;         float ss = 0.f, ss2 = 0.f;
; #pragma unroll
;         for (int j = 0; j < 8; ++j) {
;             ss += va[j][0] * va[j][0] + va[j][1] * va[j][1] + va[j][2] * va[j][2] + va[j][3] * va[j][3];
;             ss2 += vb[j][0] * vb[j][0] + vb[j][1] * vb[j][1] + vb[j][2] * vb[j][2] + vb[j][3] * vb[j][3];
;             u32x2 w; w.x = cvt_pk_bf16(va[j][0], va[j][1]); w.y = cvt_pk_bf16(va[j][2], va[j][3]);
;             *(u32x2*)(xb + (size_t)row * 2048 + j * 256 + lane * 4) = w;
;             if (has2) { u32x2 w2; w2.x = cvt_pk_bf16(vb[j][0], vb[j][1]); w2.y = cvt_pk_bf16(vb[j][2], vb[j][3]);
;                 *(u32x2*)(xb + (size_t)row2 * 2048 + j * 256 + lane * 4) = w2; }
;         }
; #pragma unroll
;         for (int o = 32; o >= 1; o >>= 1) { ss += __shfl_xor(ss, o); ss2 += __shfl_xor(ss2, o); }
;         if (lane == 0) { sumsq[row] = (u64)(ss * SS_SCALE); if (has2) sumsq[row2] = (u64)(ss2 * SS_SCALE); }
	v_add_f32_e32 v160, v160, v161
	ds_bpermute_b32 v161, v155, v160
	s_waitcnt lgkmcnt(0)
	v_add_f32_e32 v160, v160, v161
	ds_bpermute_b32 v161, v156, v160
	s_waitcnt lgkmcnt(0)
	v_add_f32_e32 v160, v160, v161
	ds_bpermute_b32 v161, v157, v160
	s_waitcnt lgkmcnt(0)
	v_add_f32_e32 v160, v160, v161
	ds_bpermute_b32 v161, v158, v160
	s_waitcnt lgkmcnt(0)
	v_add_f32_e32 v160, v160, v161
	ds_bpermute_b32 v161, v159, v160
	s_waitcnt lgkmcnt(0)
	v_add_f32_e32 v160, v160, v161
	s_and_saveexec_b64 s[20:21], s[4:5]
	v_mul_f32_e32 v162, 0x49800000, v160
	v_trunc_f32_e32 v162, v162
	v_mul_f32_e32 v163, 0x2f800000, v162
	v_floor_f32_e32 v163, v163
	v_fmac_f32_e32 v162, 0xcf800000, v163
	v_cvt_u32_f32_e32 v162, v162
	v_cvt_u32_f32_e32 v163, v163
	global_store_dwordx2 v153, v[162:163], s[16:17]
	s_or_b64 exec, exec, s[20:21]
	s_add_u32 s14, s14, 0x800000
	s_addc_u32 s15, s15, 0
	s_add_u32 s16, s16, 0x4000
	s_addc_u32 s17, s17, 0
	s_waitcnt vmcnt(26)
	v_cvt_pk_bf16_f32 v132, v2, v3
	v_cvt_pk_bf16_f32 v133, v4, v5
	global_store_dwordx2 v152, v[132:133], s[14:15]
	v_cvt_pk_bf16_f32 v134, v6, v7
	v_cvt_pk_bf16_f32 v135, v8, v9
	global_store_dwordx2 v152, v[134:135], s[14:15] offset:512
	v_cvt_pk_bf16_f32 v136, v10, v11
	v_cvt_pk_bf16_f32 v137, v12, v13
	global_store_dwordx2 v152, v[136:137], s[14:15] offset:1024
	v_cvt_pk_bf16_f32 v138, v14, v15
	v_cvt_pk_bf16_f32 v139, v16, v17
	global_store_dwordx2 v152, v[138:139], s[14:15] offset:1536
	v_cvt_pk_bf16_f32 v140, v18, v19
	v_cvt_pk_bf16_f32 v141, v20, v21
	global_store_dwordx2 v152, v[140:141], s[14:15] offset:2048
	v_cvt_pk_bf16_f32 v142, v22, v23
	v_cvt_pk_bf16_f32 v143, v24, v25
	global_store_dwordx2 v152, v[142:143], s[14:15] offset:2560
	v_cvt_pk_bf16_f32 v144, v26, v27
	v_cvt_pk_bf16_f32 v145, v28, v29
	global_store_dwordx2 v152, v[144:145], s[14:15] offset:3072
	v_cvt_pk_bf16_f32 v146, v30, v31
	v_cvt_pk_bf16_f32 v147, v32, v33
	global_store_dwordx2 v152, v[146:147], s[14:15] offset:3584
	v_mul_f32_e32 v3, v3, v3
	v_fmac_f32_e32 v3, v2, v2
	v_fmac_f32_e32 v3, v4, v4
	v_fmac_f32_e32 v3, v5, v5
	v_mul_f32_e32 v7, v7, v7
	v_fmac_f32_e32 v7, v6, v6
	v_fmac_f32_e32 v7, v8, v8
	v_fmac_f32_e32 v7, v9, v9
	v_mul_f32_e32 v11, v11, v11
	v_fmac_f32_e32 v11, v10, v10
	v_fmac_f32_e32 v11, v12, v12
	v_fmac_f32_e32 v11, v13, v13
	v_mul_f32_e32 v15, v15, v15
	v_fmac_f32_e32 v15, v14, v14
	v_fmac_f32_e32 v15, v16, v16
	v_fmac_f32_e32 v15, v17, v17
	v_mul_f32_e32 v19, v19, v19
	v_fmac_f32_e32 v19, v18, v18
	v_fmac_f32_e32 v19, v20, v20
	v_fmac_f32_e32 v19, v21, v21
	v_mul_f32_e32 v23, v23, v23
	v_fmac_f32_e32 v23, v22, v22
	v_fmac_f32_e32 v23, v24, v24
	v_fmac_f32_e32 v23, v25, v25
	v_mul_f32_e32 v27, v27, v27
	v_fmac_f32_e32 v27, v26, v26
	v_fmac_f32_e32 v27, v28, v28
	v_fmac_f32_e32 v27, v29, v29
	v_mul_f32_e32 v31, v31, v31
	v_fmac_f32_e32 v31, v30, v30
	v_fmac_f32_e32 v31, v32, v32
	v_fmac_f32_e32 v31, v33, v33
	v_add_f32_e32 v160, v3, v7
	v_add_f32_e32 v160, v160, v11
	v_add_f32_e32 v160, v160, v15
	v_add_f32_e32 v160, v160, v19
	v_add_f32_e32 v160, v160, v23
	v_add_f32_e32 v160, v160, v27
	v_add_f32_e32 v160, v160, v31
	ds_bpermute_b32 v161, v154, v160
	s_waitcnt lgkmcnt(0)
	v_add_f32_e32 v160, v160, v161
	ds_bpermute_b32 v161, v155, v160
	s_waitcnt lgkmcnt(0)
	v_add_f32_e32 v160, v160, v161
	ds_bpermute_b32 v161, v156, v160
	s_waitcnt lgkmcnt(0)
	v_add_f32_e32 v160, v160, v161
	ds_bpermute_b32 v161, v157, v160
	s_waitcnt lgkmcnt(0)
	v_add_f32_e32 v160, v160, v161
	ds_bpermute_b32 v161, v158, v160
	s_waitcnt lgkmcnt(0)
	v_add_f32_e32 v160, v160, v161
	ds_bpermute_b32 v161, v159, v160
	s_waitcnt lgkmcnt(0)
	v_add_f32_e32 v160, v160, v161
	s_and_saveexec_b64 s[20:21], s[4:5]
	v_mul_f32_e32 v162, 0x49800000, v160
	v_trunc_f32_e32 v162, v162
	v_mul_f32_e32 v163, 0x2f800000, v162
	v_floor_f32_e32 v163, v163
	v_fmac_f32_e32 v162, 0xcf800000, v163
	v_cvt_u32_f32_e32 v162, v162
	v_cvt_u32_f32_e32 v163, v163
	global_store_dwordx2 v153, v[162:163], s[16:17]
	s_or_b64 exec, exec, s[20:21]
	s_add_u32 s14, s14, 0x800000
	s_addc_u32 s15, s15, 0
	s_add_u32 s16, s16, 0x4000
	s_addc_u32 s17, s17, 0
	s_waitcnt vmcnt(18)
	v_cvt_pk_bf16_f32 v132, v100, v101
	v_cvt_pk_bf16_f32 v133, v102, v103
	global_store_dwordx2 v152, v[132:133], s[14:15]
	v_cvt_pk_bf16_f32 v134, v104, v105
	v_cvt_pk_bf16_f32 v135, v106, v107
	global_store_dwordx2 v152, v[134:135], s[14:15] offset:512
	v_cvt_pk_bf16_f32 v136, v108, v109
	v_cvt_pk_bf16_f32 v137, v110, v111
	global_store_dwordx2 v152, v[136:137], s[14:15] offset:1024
	v_cvt_pk_bf16_f32 v138, v112, v113
	v_cvt_pk_bf16_f32 v139, v114, v115
	global_store_dwordx2 v152, v[138:139], s[14:15] offset:1536
	v_cvt_pk_bf16_f32 v140, v116, v117
	v_cvt_pk_bf16_f32 v141, v118, v119
	global_store_dwordx2 v152, v[140:141], s[14:15] offset:2048
	v_cvt_pk_bf16_f32 v142, v120, v121
	v_cvt_pk_bf16_f32 v143, v122, v123
	global_store_dwordx2 v152, v[142:143], s[14:15] offset:2560
	v_cvt_pk_bf16_f32 v144, v124, v125
	v_cvt_pk_bf16_f32 v145, v126, v127
	global_store_dwordx2 v152, v[144:145], s[14:15] offset:3072
	v_cvt_pk_bf16_f32 v146, v128, v129
	v_cvt_pk_bf16_f32 v147, v130, v131
	global_store_dwordx2 v152, v[146:147], s[14:15] offset:3584
	v_mul_f32_e32 v101, v101, v101
	v_fmac_f32_e32 v101, v100, v100
	v_fmac_f32_e32 v101, v102, v102
	v_fmac_f32_e32 v101, v103, v103
	v_mul_f32_e32 v105, v105, v105
	v_fmac_f32_e32 v105, v104, v104
	v_fmac_f32_e32 v105, v106, v106
	v_fmac_f32_e32 v105, v107, v107
	v_mul_f32_e32 v109, v109, v109
	v_fmac_f32_e32 v109, v108, v108
	v_fmac_f32_e32 v109, v110, v110
	v_fmac_f32_e32 v109, v111, v111
	v_mul_f32_e32 v113, v113, v113
	v_fmac_f32_e32 v113, v112, v112
	v_fmac_f32_e32 v113, v114, v114
	v_fmac_f32_e32 v113, v115, v115
	v_mul_f32_e32 v117, v117, v117
	v_fmac_f32_e32 v117, v116, v116
	v_fmac_f32_e32 v117, v118, v118
	v_fmac_f32_e32 v117, v119, v119
	v_mul_f32_e32 v121, v121, v121
	v_fmac_f32_e32 v121, v120, v120
	v_fmac_f32_e32 v121, v122, v122
	v_fmac_f32_e32 v121, v123, v123
	v_mul_f32_e32 v125, v125, v125
	v_fmac_f32_e32 v125, v124, v124
	v_fmac_f32_e32 v125, v126, v126
	v_fmac_f32_e32 v125, v127, v127
	v_mul_f32_e32 v129, v129, v129
	v_fmac_f32_e32 v129, v128, v128
	v_fmac_f32_e32 v129, v130, v130
	v_fmac_f32_e32 v129, v131, v131
	v_add_f32_e32 v160, v101, v105
	v_add_f32_e32 v160, v160, v109
	v_add_f32_e32 v160, v160, v113
	v_add_f32_e32 v160, v160, v117
	v_add_f32_e32 v160, v160, v121
	v_add_f32_e32 v160, v160, v125
	v_add_f32_e32 v160, v160, v129
	ds_bpermute_b32 v161, v154, v160
	s_waitcnt lgkmcnt(0)
; __device__ __forceinline__ unsigned cvt_pk_bf16(float lo, float hi) { unsigned r; asm("v_cvt_pk_bf16_f32 %0, %1, %2" : "=v"(r) : "v"(lo), "v"(hi)); return r; }
; __device__ __forceinline__ void phase_prep(const Params& p, LAS unsigned char* lds) {
;     ...
;     for (int row = blockIdx.x * 8 + wid; row < T; row += gridDim.x * 16) {
;         const int row2 = row + gridDim.x * 8; const bool has2 = row2 < T;
;         const float* xr = row < TP ? p.x_prompt + (size_t)row * 2048 : p.x_sample + (size_t)(row - TP) * 2048;
;         const float* xr2 = has2 ? (row2 < TP ? p.x_prompt + (size_t)row2 * 2048 : p.x_sample + (size_t)(row2 - TP) * 2048) : xr;
;         f32x4 va[8], vb[8];
; #pragma unroll
;         for (int j = 0; j < 8; ++j) { va[j] = *(const f32x4*)(xr + j * 256 + lane * 4); vb[j] = *(const f32x4*)(xr2 + j * 256 + lane * 4); }
;         float ss = 0.f, ss2 = 0.f;
; #pragma unroll
;         for (int j = 0; j < 8; ++j) {
;             ss += va[j][0] * va[j][0] + va[j][1] * va[j][1] + va[j][2] * va[j][2] + va[j][3] * va[j][3];
;             ss2 += vb[j][0] * vb[j][0] + vb[j][1] * vb[j][1] + vb[j][2] * vb[j][2] + vb[j][3] * vb[j][3];
;             u32x2 w; w.x = cvt_pk_bf16(va[j][0], va[j][1]); w.y = cvt_pk_bf16(va[j][2], va[j][3]);
;             *(u32x2*)(xb + (size_t)row * 2048 + j * 256 + lane * 4) = w;
;             if (has2) { u32x2 w2; w2.x = cvt_pk_bf16(vb[j][0], vb[j][1]); w2.y = cvt_pk_bf16(vb[j][2], vb[j][3]);
;                 *(u32x2*)(xb + (size_t)row2 * 2048 + j * 256 + lane * 4) = w2; }
;         }
; #pragma unroll
;         for (int o = 32; o >= 1; o >>= 1) { ss += __shfl_xor(ss, o); ss2 += __shfl_xor(ss2, o); }
;         if (lane == 0) { sumsq[row] = (u64)(ss * SS_SCALE); if (has2) sumsq[row2] = (u64)(ss2 * SS_SCALE); }
;     }
	v_add_f32_e32 v160, v160, v161
	ds_bpermute_b32 v161, v155, v160
	s_waitcnt lgkmcnt(0)
	v_add_f32_e32 v160, v160, v161
	ds_bpermute_b32 v161, v156, v160
	s_waitcnt lgkmcnt(0)
	v_add_f32_e32 v160, v160, v161
	ds_bpermute_b32 v161, v157, v160
	s_waitcnt lgkmcnt(0)
	v_add_f32_e32 v160, v160, v161
	ds_bpermute_b32 v161, v158, v160
	s_waitcnt lgkmcnt(0)
	v_add_f32_e32 v160, v160, v161
	ds_bpermute_b32 v161, v159, v160
	s_waitcnt lgkmcnt(0)
	v_add_f32_e32 v160, v160, v161
	s_and_saveexec_b64 s[20:21], s[4:5]
	v_mul_f32_e32 v162, 0x49800000, v160
	v_trunc_f32_e32 v162, v162
	v_mul_f32_e32 v163, 0x2f800000, v162
	v_floor_f32_e32 v163, v163
	v_fmac_f32_e32 v162, 0xcf800000, v163
	v_cvt_u32_f32_e32 v162, v162
	v_cvt_u32_f32_e32 v163, v163
	global_store_dwordx2 v153, v[162:163], s[16:17]
	s_or_b64 exec, exec, s[20:21]
	s_add_u32 s14, s14, 0x800000
	s_addc_u32 s15, s15, 0
	s_add_u32 s16, s16, 0x4000
	s_addc_u32 s17, s17, 0
	s_cmpk_lt_u32 s18, 0x200
	s_cbranch_scc0 .Lxprep_done
	s_lshl_b32 s19, s18, 13
	s_add_u32 s12, s62, s19
	s_addc_u32 s13, s63, 0
	global_load_dwordx4 v[164:167], v150, s[12:13]
	global_load_dwordx4 v[168:171], v150, s[12:13] offset:1024
	global_load_dwordx4 v[172:175], v150, s[12:13] offset:2048
	global_load_dwordx4 v[176:179], v150, s[12:13] offset:3072
	global_load_dwordx4 v[180:183], v151, s[12:13]
	global_load_dwordx4 v[184:187], v151, s[12:13] offset:1024
	global_load_dwordx4 v[188:191], v151, s[12:13] offset:2048
	global_load_dwordx4 v[192:195], v151, s[12:13] offset:3072
	s_waitcnt vmcnt(0)
	v_cvt_pk_bf16_f32 v132, v164, v165
	v_cvt_pk_bf16_f32 v133, v166, v167
	global_store_dwordx2 v152, v[132:133], s[14:15]
	v_cvt_pk_bf16_f32 v134, v168, v169
	v_cvt_pk_bf16_f32 v135, v170, v171
	global_store_dwordx2 v152, v[134:135], s[14:15] offset:512
	v_cvt_pk_bf16_f32 v136, v172, v173
	v_cvt_pk_bf16_f32 v137, v174, v175
	global_store_dwordx2 v152, v[136:137], s[14:15] offset:1024
	v_cvt_pk_bf16_f32 v138, v176, v177
	v_cvt_pk_bf16_f32 v139, v178, v179
	global_store_dwordx2 v152, v[138:139], s[14:15] offset:1536
	v_cvt_pk_bf16_f32 v140, v180, v181
	v_cvt_pk_bf16_f32 v141, v182, v183
	global_store_dwordx2 v152, v[140:141], s[14:15] offset:2048
	v_cvt_pk_bf16_f32 v142, v184, v185
	v_cvt_pk_bf16_f32 v143, v186, v187
	global_store_dwordx2 v152, v[142:143], s[14:15] offset:2560
	v_cvt_pk_bf16_f32 v144, v188, v189
	v_cvt_pk_bf16_f32 v145, v190, v191
	global_store_dwordx2 v152, v[144:145], s[14:15] offset:3072
	v_cvt_pk_bf16_f32 v146, v192, v193
	v_cvt_pk_bf16_f32 v147, v194, v195
	global_store_dwordx2 v152, v[146:147], s[14:15] offset:3584
	v_mul_f32_e32 v165, v165, v165
	v_fmac_f32_e32 v165, v164, v164
	v_fmac_f32_e32 v165, v166, v166
	v_fmac_f32_e32 v165, v167, v167
	v_mul_f32_e32 v169, v169, v169
	v_fmac_f32_e32 v169, v168, v168
	v_fmac_f32_e32 v169, v170, v170
	v_fmac_f32_e32 v169, v171, v171
	v_mul_f32_e32 v173, v173, v173
	v_fmac_f32_e32 v173, v172, v172
	v_fmac_f32_e32 v173, v174, v174
	v_fmac_f32_e32 v173, v175, v175
	v_mul_f32_e32 v177, v177, v177
	v_fmac_f32_e32 v177, v176, v176
	v_fmac_f32_e32 v177, v178, v178
	v_fmac_f32_e32 v177, v179, v179
	v_mul_f32_e32 v181, v181, v181
	v_fmac_f32_e32 v181, v180, v180
	v_fmac_f32_e32 v181, v182, v182
	v_fmac_f32_e32 v181, v183, v183
	v_mul_f32_e32 v185, v185, v185
	v_fmac_f32_e32 v185, v184, v184
	v_fmac_f32_e32 v185, v186, v186
	v_fmac_f32_e32 v185, v187, v187
	v_mul_f32_e32 v189, v189, v189
	v_fmac_f32_e32 v189, v188, v188
	v_fmac_f32_e32 v189, v190, v190
	v_fmac_f32_e32 v189, v191, v191
	v_mul_f32_e32 v193, v193, v193
	v_fmac_f32_e32 v193, v192, v192
	v_fmac_f32_e32 v193, v194, v194
	v_fmac_f32_e32 v193, v195, v195
	v_add_f32_e32 v160, v165, v169
	v_add_f32_e32 v160, v160, v173
	v_add_f32_e32 v160, v160, v177
	v_add_f32_e32 v160, v160, v181
	v_add_f32_e32 v160, v160, v185
	v_add_f32_e32 v160, v160, v189
	v_add_f32_e32 v160, v160, v193
	ds_bpermute_b32 v161, v154, v160
	s_waitcnt lgkmcnt(0)
	v_add_f32_e32 v160, v160, v161
	ds_bpermute_b32 v161, v155, v160
	s_waitcnt lgkmcnt(0)
	v_add_f32_e32 v160, v160, v161
	ds_bpermute_b32 v161, v156, v160
	s_waitcnt lgkmcnt(0)
	v_add_f32_e32 v160, v160, v161
	ds_bpermute_b32 v161, v157, v160
	s_waitcnt lgkmcnt(0)
	v_add_f32_e32 v160, v160, v161
	ds_bpermute_b32 v161, v158, v160
	s_waitcnt lgkmcnt(0)
	v_add_f32_e32 v160, v160, v161
	ds_bpermute_b32 v161, v159, v160
	s_waitcnt lgkmcnt(0)
	v_add_f32_e32 v160, v160, v161
	s_and_saveexec_b64 s[20:21], s[4:5]
	v_mul_f32_e32 v162, 0x49800000, v160
	v_trunc_f32_e32 v162, v162
	v_mul_f32_e32 v163, 0x2f800000, v162
	v_floor_f32_e32 v163, v163
	v_fmac_f32_e32 v162, 0xcf800000, v163
	v_cvt_u32_f32_e32 v162, v162
	v_cvt_u32_f32_e32 v163, v163
	global_store_dwordx2 v153, v[162:163], s[16:17]
	s_or_b64 exec, exec, s[20:21]
.Lxprep_done:
.LBB0_44:
	s_or_b64 exec, exec, s[0:1]
	s_mov_b32 s0, 0x20000
	v_cmp_gt_i32_e32 vcc, s0, v64
	s_and_saveexec_b64 s[0:1], vcc
	s_cbranch_execz .LBB0_47
	s_lshl_b32 s2, s3, 9
	s_mov_b64 s[4:5], 0
	s_movk_i32 s6, 0x6040
	s_waitcnt lgkmcnt(0)
	v_mov_b64_e32 v[0:1], s[66:67]
	v_mov_b32_e32 v3, 0
	s_movk_i32 s7, 0x3000
	s_mov_b32 s12, 0x1ffff
	v_mov_b32_e32 v4, v64
